# ln2: expert-output gathers of a token issued in batches of up to 4 selected experts before consuming (same accumulation order), instead of one exposed memory latency per expert
# speedup vs baseline: 1.0187x; 1.0119x over previous
.LBB0_1400:
.Lg_scan0:
	v_readlane_b32 s2, v76, s7
	s_add_i32 s7, s7, 1
	s_cmp_lt_i32 s2, 0
	s_cbranch_scc0 .Lg_issue0
	s_cmp_lt_u32 s7, 16
	s_cbranch_scc1 .Lg_scan0
	s_branch .LBB0_1393
.Lg_issue0:
	v_mov_b32_e32 v40, s2
	v_lshlrev_b64 v[94:95], 10, v[40:41]
	v_lshl_add_u64 v[94:95], v[36:37], 0, v[94:95]
	global_load_dword v96, v[94:95], off
	global_load_dword v97, v[94:95], off offset:256
	global_load_dword v98, v[94:95], off offset:512
	global_load_dword v99, v[94:95], off offset:768
.Lg_scan1:
	s_cmp_lt_u32 s7, 16
	s_cbranch_scc0 .Lg_cons1
	v_readlane_b32 s2, v76, s7
	s_add_i32 s7, s7, 1
	s_cmp_lt_i32 s2, 0
	s_cbranch_scc1 .Lg_scan1
	v_mov_b32_e32 v40, s2
	v_lshlrev_b64 v[94:95], 10, v[40:41]
	v_lshl_add_u64 v[94:95], v[36:37], 0, v[94:95]
	global_load_dword v100, v[94:95], off
	global_load_dword v101, v[94:95], off offset:256
	global_load_dword v102, v[94:95], off offset:512
	global_load_dword v103, v[94:95], off offset:768
.Lg_scan2:
	s_cmp_lt_u32 s7, 16
	s_cbranch_scc0 .Lg_cons2
	v_readlane_b32 s2, v76, s7
	s_add_i32 s7, s7, 1
	s_cmp_lt_i32 s2, 0
	s_cbranch_scc1 .Lg_scan2
	v_mov_b32_e32 v40, s2
	v_lshlrev_b64 v[94:95], 10, v[40:41]
	v_lshl_add_u64 v[94:95], v[36:37], 0, v[94:95]
	global_load_dword v104, v[94:95], off
	global_load_dword v105, v[94:95], off offset:256
	global_load_dword v106, v[94:95], off offset:512
	global_load_dword v107, v[94:95], off offset:768
.Lg_scan3:
	s_cmp_lt_u32 s7, 16
	s_cbranch_scc0 .Lg_cons3
	v_readlane_b32 s2, v76, s7
	s_add_i32 s7, s7, 1
	s_cmp_lt_i32 s2, 0
	s_cbranch_scc1 .Lg_scan3
	v_mov_b32_e32 v40, s2
	v_lshlrev_b64 v[94:95], 10, v[40:41]
	v_lshl_add_u64 v[94:95], v[36:37], 0, v[94:95]
	global_load_dword v108, v[94:95], off
	global_load_dword v109, v[94:95], off offset:256
	global_load_dword v110, v[94:95], off offset:512
	global_load_dword v111, v[94:95], off offset:768
.Lg_cons4:
	s_waitcnt vmcnt(12)
	v_cvt_f32_fp8_e32 v78, v96
	v_cvt_f32_fp8_sdwa v79, v96 src0_sel:BYTE_1
	v_cvt_f32_fp8_sdwa v80, v96 src0_sel:BYTE_2
	v_cvt_f32_fp8_sdwa v81, v96 src0_sel:BYTE_3
	v_cvt_f32_fp8_e32 v82, v97
	v_cvt_f32_fp8_sdwa v83, v97 src0_sel:BYTE_1
	v_cvt_f32_fp8_sdwa v84, v97 src0_sel:BYTE_2
	v_cvt_f32_fp8_sdwa v85, v97 src0_sel:BYTE_3
	v_cvt_f32_fp8_e32 v86, v98
	v_cvt_f32_fp8_sdwa v87, v98 src0_sel:BYTE_1
	v_cvt_f32_fp8_sdwa v88, v98 src0_sel:BYTE_2
	v_cvt_f32_fp8_sdwa v89, v98 src0_sel:BYTE_3
	v_cvt_f32_fp8_e32 v90, v99
	v_cvt_f32_fp8_sdwa v91, v99 src0_sel:BYTE_1
	v_cvt_f32_fp8_sdwa v92, v99 src0_sel:BYTE_2
	v_cvt_f32_fp8_sdwa v93, v99 src0_sel:BYTE_3
	v_pk_fma_f32 v[64:65], v[78:79], s[6:7], v[64:65] op_sel_hi:[1,0,1]
	v_pk_fma_f32 v[62:63], v[80:81], s[6:7], v[62:63] op_sel_hi:[1,0,1]
	v_pk_fma_f32 v[60:61], v[82:83], s[6:7], v[60:61] op_sel_hi:[1,0,1]
	v_pk_fma_f32 v[58:59], v[84:85], s[6:7], v[58:59] op_sel_hi:[1,0,1]
	v_pk_fma_f32 v[56:57], v[86:87], s[6:7], v[56:57] op_sel_hi:[1,0,1]
	v_pk_fma_f32 v[54:55], v[88:89], s[6:7], v[54:55] op_sel_hi:[1,0,1]
	v_pk_fma_f32 v[50:51], v[90:91], s[6:7], v[50:51] op_sel_hi:[1,0,1]
	v_pk_fma_f32 v[52:53], v[92:93], s[6:7], v[52:53] op_sel_hi:[1,0,1]
	s_waitcnt vmcnt(8)
	v_cvt_f32_fp8_e32 v78, v100
	v_cvt_f32_fp8_sdwa v79, v100 src0_sel:BYTE_1
	v_cvt_f32_fp8_sdwa v80, v100 src0_sel:BYTE_2
	v_cvt_f32_fp8_sdwa v81, v100 src0_sel:BYTE_3
	v_cvt_f32_fp8_e32 v82, v101
	v_cvt_f32_fp8_sdwa v83, v101 src0_sel:BYTE_1
	v_cvt_f32_fp8_sdwa v84, v101 src0_sel:BYTE_2
	v_cvt_f32_fp8_sdwa v85, v101 src0_sel:BYTE_3
	v_cvt_f32_fp8_e32 v86, v102
	v_cvt_f32_fp8_sdwa v87, v102 src0_sel:BYTE_1
	v_cvt_f32_fp8_sdwa v88, v102 src0_sel:BYTE_2
	v_cvt_f32_fp8_sdwa v89, v102 src0_sel:BYTE_3
	v_cvt_f32_fp8_e32 v90, v103
	v_cvt_f32_fp8_sdwa v91, v103 src0_sel:BYTE_1
	v_cvt_f32_fp8_sdwa v92, v103 src0_sel:BYTE_2
	v_cvt_f32_fp8_sdwa v93, v103 src0_sel:BYTE_3
	v_pk_fma_f32 v[64:65], v[78:79], s[6:7], v[64:65] op_sel_hi:[1,0,1]
	v_pk_fma_f32 v[62:63], v[80:81], s[6:7], v[62:63] op_sel_hi:[1,0,1]
	v_pk_fma_f32 v[60:61], v[82:83], s[6:7], v[60:61] op_sel_hi:[1,0,1]
	v_pk_fma_f32 v[58:59], v[84:85], s[6:7], v[58:59] op_sel_hi:[1,0,1]
	v_pk_fma_f32 v[56:57], v[86:87], s[6:7], v[56:57] op_sel_hi:[1,0,1]
	v_pk_fma_f32 v[54:55], v[88:89], s[6:7], v[54:55] op_sel_hi:[1,0,1]
	v_pk_fma_f32 v[50:51], v[90:91], s[6:7], v[50:51] op_sel_hi:[1,0,1]
	v_pk_fma_f32 v[52:53], v[92:93], s[6:7], v[52:53] op_sel_hi:[1,0,1]
	s_waitcnt vmcnt(4)
	v_cvt_f32_fp8_e32 v78, v104
	v_cvt_f32_fp8_sdwa v79, v104 src0_sel:BYTE_1
	v_cvt_f32_fp8_sdwa v80, v104 src0_sel:BYTE_2
	v_cvt_f32_fp8_sdwa v81, v104 src0_sel:BYTE_3
	v_cvt_f32_fp8_e32 v82, v105
	v_cvt_f32_fp8_sdwa v83, v105 src0_sel:BYTE_1
	v_cvt_f32_fp8_sdwa v84, v105 src0_sel:BYTE_2
	v_cvt_f32_fp8_sdwa v85, v105 src0_sel:BYTE_3
	v_cvt_f32_fp8_e32 v86, v106
	v_cvt_f32_fp8_sdwa v87, v106 src0_sel:BYTE_1
	v_cvt_f32_fp8_sdwa v88, v106 src0_sel:BYTE_2
	v_cvt_f32_fp8_sdwa v89, v106 src0_sel:BYTE_3
	v_cvt_f32_fp8_e32 v90, v107
	v_cvt_f32_fp8_sdwa v91, v107 src0_sel:BYTE_1
	v_cvt_f32_fp8_sdwa v92, v107 src0_sel:BYTE_2
	v_cvt_f32_fp8_sdwa v93, v107 src0_sel:BYTE_3
	v_pk_fma_f32 v[64:65], v[78:79], s[6:7], v[64:65] op_sel_hi:[1,0,1]
	v_pk_fma_f32 v[62:63], v[80:81], s[6:7], v[62:63] op_sel_hi:[1,0,1]
	v_pk_fma_f32 v[60:61], v[82:83], s[6:7], v[60:61] op_sel_hi:[1,0,1]
	v_pk_fma_f32 v[58:59], v[84:85], s[6:7], v[58:59] op_sel_hi:[1,0,1]
	v_pk_fma_f32 v[56:57], v[86:87], s[6:7], v[56:57] op_sel_hi:[1,0,1]
	v_pk_fma_f32 v[54:55], v[88:89], s[6:7], v[54:55] op_sel_hi:[1,0,1]
	v_pk_fma_f32 v[50:51], v[90:91], s[6:7], v[50:51] op_sel_hi:[1,0,1]
	v_pk_fma_f32 v[52:53], v[92:93], s[6:7], v[52:53] op_sel_hi:[1,0,1]
	s_waitcnt vmcnt(0)
	v_cvt_f32_fp8_e32 v78, v108
	v_cvt_f32_fp8_sdwa v79, v108 src0_sel:BYTE_1
	v_cvt_f32_fp8_sdwa v80, v108 src0_sel:BYTE_2
	v_cvt_f32_fp8_sdwa v81, v108 src0_sel:BYTE_3
	v_cvt_f32_fp8_e32 v82, v109
	v_cvt_f32_fp8_sdwa v83, v109 src0_sel:BYTE_1
	v_cvt_f32_fp8_sdwa v84, v109 src0_sel:BYTE_2
	v_cvt_f32_fp8_sdwa v85, v109 src0_sel:BYTE_3
	v_cvt_f32_fp8_e32 v86, v110
	v_cvt_f32_fp8_sdwa v87, v110 src0_sel:BYTE_1
	v_cvt_f32_fp8_sdwa v88, v110 src0_sel:BYTE_2
	v_cvt_f32_fp8_sdwa v89, v110 src0_sel:BYTE_3
	v_cvt_f32_fp8_e32 v90, v111
	v_cvt_f32_fp8_sdwa v91, v111 src0_sel:BYTE_1
	v_cvt_f32_fp8_sdwa v92, v111 src0_sel:BYTE_2
	v_cvt_f32_fp8_sdwa v93, v111 src0_sel:BYTE_3
	v_pk_fma_f32 v[64:65], v[78:79], s[6:7], v[64:65] op_sel_hi:[1,0,1]
	v_pk_fma_f32 v[62:63], v[80:81], s[6:7], v[62:63] op_sel_hi:[1,0,1]
	v_pk_fma_f32 v[60:61], v[82:83], s[6:7], v[60:61] op_sel_hi:[1,0,1]
	v_pk_fma_f32 v[58:59], v[84:85], s[6:7], v[58:59] op_sel_hi:[1,0,1]
	v_pk_fma_f32 v[56:57], v[86:87], s[6:7], v[56:57] op_sel_hi:[1,0,1]
	v_pk_fma_f32 v[54:55], v[88:89], s[6:7], v[54:55] op_sel_hi:[1,0,1]
	v_pk_fma_f32 v[50:51], v[90:91], s[6:7], v[50:51] op_sel_hi:[1,0,1]
	v_pk_fma_f32 v[52:53], v[92:93], s[6:7], v[52:53] op_sel_hi:[1,0,1]
	s_cmp_lt_u32 s7, 16
	s_cbranch_scc1 .Lg_scan0
	s_branch .LBB0_1393
.Lg_cons3:
	s_waitcnt vmcnt(8)
	v_cvt_f32_fp8_e32 v78, v96
	v_cvt_f32_fp8_sdwa v79, v96 src0_sel:BYTE_1
	v_cvt_f32_fp8_sdwa v80, v96 src0_sel:BYTE_2
	v_cvt_f32_fp8_sdwa v81, v96 src0_sel:BYTE_3
	v_cvt_f32_fp8_e32 v82, v97
	v_cvt_f32_fp8_sdwa v83, v97 src0_sel:BYTE_1
	v_cvt_f32_fp8_sdwa v84, v97 src0_sel:BYTE_2
	v_cvt_f32_fp8_sdwa v85, v97 src0_sel:BYTE_3
	v_cvt_f32_fp8_e32 v86, v98
	v_cvt_f32_fp8_sdwa v87, v98 src0_sel:BYTE_1
	v_cvt_f32_fp8_sdwa v88, v98 src0_sel:BYTE_2
	v_cvt_f32_fp8_sdwa v89, v98 src0_sel:BYTE_3
	v_cvt_f32_fp8_e32 v90, v99
	v_cvt_f32_fp8_sdwa v91, v99 src0_sel:BYTE_1
	v_cvt_f32_fp8_sdwa v92, v99 src0_sel:BYTE_2
	v_cvt_f32_fp8_sdwa v93, v99 src0_sel:BYTE_3
	v_pk_fma_f32 v[64:65], v[78:79], s[6:7], v[64:65] op_sel_hi:[1,0,1]
	v_pk_fma_f32 v[62:63], v[80:81], s[6:7], v[62:63] op_sel_hi:[1,0,1]
	v_pk_fma_f32 v[60:61], v[82:83], s[6:7], v[60:61] op_sel_hi:[1,0,1]
	v_pk_fma_f32 v[58:59], v[84:85], s[6:7], v[58:59] op_sel_hi:[1,0,1]
	v_pk_fma_f32 v[56:57], v[86:87], s[6:7], v[56:57] op_sel_hi:[1,0,1]
	v_pk_fma_f32 v[54:55], v[88:89], s[6:7], v[54:55] op_sel_hi:[1,0,1]
	v_pk_fma_f32 v[50:51], v[90:91], s[6:7], v[50:51] op_sel_hi:[1,0,1]
	v_pk_fma_f32 v[52:53], v[92:93], s[6:7], v[52:53] op_sel_hi:[1,0,1]
	s_waitcnt vmcnt(4)
	v_cvt_f32_fp8_e32 v78, v100
	v_cvt_f32_fp8_sdwa v79, v100 src0_sel:BYTE_1
	v_cvt_f32_fp8_sdwa v80, v100 src0_sel:BYTE_2
	v_cvt_f32_fp8_sdwa v81, v100 src0_sel:BYTE_3
	v_cvt_f32_fp8_e32 v82, v101
	v_cvt_f32_fp8_sdwa v83, v101 src0_sel:BYTE_1
	v_cvt_f32_fp8_sdwa v84, v101 src0_sel:BYTE_2
	v_cvt_f32_fp8_sdwa v85, v101 src0_sel:BYTE_3
	v_cvt_f32_fp8_e32 v86, v102
	v_cvt_f32_fp8_sdwa v87, v102 src0_sel:BYTE_1
	v_cvt_f32_fp8_sdwa v88, v102 src0_sel:BYTE_2
	v_cvt_f32_fp8_sdwa v89, v102 src0_sel:BYTE_3
	v_cvt_f32_fp8_e32 v90, v103
	v_cvt_f32_fp8_sdwa v91, v103 src0_sel:BYTE_1
	v_cvt_f32_fp8_sdwa v92, v103 src0_sel:BYTE_2
	v_cvt_f32_fp8_sdwa v93, v103 src0_sel:BYTE_3
	v_pk_fma_f32 v[64:65], v[78:79], s[6:7], v[64:65] op_sel_hi:[1,0,1]
	v_pk_fma_f32 v[62:63], v[80:81], s[6:7], v[62:63] op_sel_hi:[1,0,1]
	v_pk_fma_f32 v[60:61], v[82:83], s[6:7], v[60:61] op_sel_hi:[1,0,1]
	v_pk_fma_f32 v[58:59], v[84:85], s[6:7], v[58:59] op_sel_hi:[1,0,1]
	v_pk_fma_f32 v[56:57], v[86:87], s[6:7], v[56:57] op_sel_hi:[1,0,1]
	v_pk_fma_f32 v[54:55], v[88:89], s[6:7], v[54:55] op_sel_hi:[1,0,1]
	v_pk_fma_f32 v[50:51], v[90:91], s[6:7], v[50:51] op_sel_hi:[1,0,1]
	v_pk_fma_f32 v[52:53], v[92:93], s[6:7], v[52:53] op_sel_hi:[1,0,1]
	s_waitcnt vmcnt(0)
	v_cvt_f32_fp8_e32 v78, v104
	v_cvt_f32_fp8_sdwa v79, v104 src0_sel:BYTE_1
	v_cvt_f32_fp8_sdwa v80, v104 src0_sel:BYTE_2
	v_cvt_f32_fp8_sdwa v81, v104 src0_sel:BYTE_3
	v_cvt_f32_fp8_e32 v82, v105
	v_cvt_f32_fp8_sdwa v83, v105 src0_sel:BYTE_1
	v_cvt_f32_fp8_sdwa v84, v105 src0_sel:BYTE_2
	v_cvt_f32_fp8_sdwa v85, v105 src0_sel:BYTE_3
	v_cvt_f32_fp8_e32 v86, v106
	v_cvt_f32_fp8_sdwa v87, v106 src0_sel:BYTE_1
	v_cvt_f32_fp8_sdwa v88, v106 src0_sel:BYTE_2
	v_cvt_f32_fp8_sdwa v89, v106 src0_sel:BYTE_3
	v_cvt_f32_fp8_e32 v90, v107
	v_cvt_f32_fp8_sdwa v91, v107 src0_sel:BYTE_1
	v_cvt_f32_fp8_sdwa v92, v107 src0_sel:BYTE_2
	v_cvt_f32_fp8_sdwa v93, v107 src0_sel:BYTE_3
	v_pk_fma_f32 v[64:65], v[78:79], s[6:7], v[64:65] op_sel_hi:[1,0,1]
	v_pk_fma_f32 v[62:63], v[80:81], s[6:7], v[62:63] op_sel_hi:[1,0,1]
	v_pk_fma_f32 v[60:61], v[82:83], s[6:7], v[60:61] op_sel_hi:[1,0,1]
	v_pk_fma_f32 v[58:59], v[84:85], s[6:7], v[58:59] op_sel_hi:[1,0,1]
	v_pk_fma_f32 v[56:57], v[86:87], s[6:7], v[56:57] op_sel_hi:[1,0,1]
	v_pk_fma_f32 v[54:55], v[88:89], s[6:7], v[54:55] op_sel_hi:[1,0,1]
	v_pk_fma_f32 v[50:51], v[90:91], s[6:7], v[50:51] op_sel_hi:[1,0,1]
	v_pk_fma_f32 v[52:53], v[92:93], s[6:7], v[52:53] op_sel_hi:[1,0,1]
	s_branch .LBB0_1393
.Lg_cons2:
	s_waitcnt vmcnt(4)
	v_cvt_f32_fp8_e32 v78, v96
	v_cvt_f32_fp8_sdwa v79, v96 src0_sel:BYTE_1
	v_cvt_f32_fp8_sdwa v80, v96 src0_sel:BYTE_2
	v_cvt_f32_fp8_sdwa v81, v96 src0_sel:BYTE_3
	v_cvt_f32_fp8_e32 v82, v97
	v_cvt_f32_fp8_sdwa v83, v97 src0_sel:BYTE_1
	v_cvt_f32_fp8_sdwa v84, v97 src0_sel:BYTE_2
	v_cvt_f32_fp8_sdwa v85, v97 src0_sel:BYTE_3
	v_cvt_f32_fp8_e32 v86, v98
	v_cvt_f32_fp8_sdwa v87, v98 src0_sel:BYTE_1
	v_cvt_f32_fp8_sdwa v88, v98 src0_sel:BYTE_2
	v_cvt_f32_fp8_sdwa v89, v98 src0_sel:BYTE_3
	v_cvt_f32_fp8_e32 v90, v99
	v_cvt_f32_fp8_sdwa v91, v99 src0_sel:BYTE_1
	v_cvt_f32_fp8_sdwa v92, v99 src0_sel:BYTE_2
	v_cvt_f32_fp8_sdwa v93, v99 src0_sel:BYTE_3
	v_pk_fma_f32 v[64:65], v[78:79], s[6:7], v[64:65] op_sel_hi:[1,0,1]
	v_pk_fma_f32 v[62:63], v[80:81], s[6:7], v[62:63] op_sel_hi:[1,0,1]
	v_pk_fma_f32 v[60:61], v[82:83], s[6:7], v[60:61] op_sel_hi:[1,0,1]
	v_pk_fma_f32 v[58:59], v[84:85], s[6:7], v[58:59] op_sel_hi:[1,0,1]
	v_pk_fma_f32 v[56:57], v[86:87], s[6:7], v[56:57] op_sel_hi:[1,0,1]
	v_pk_fma_f32 v[54:55], v[88:89], s[6:7], v[54:55] op_sel_hi:[1,0,1]
	v_pk_fma_f32 v[50:51], v[90:91], s[6:7], v[50:51] op_sel_hi:[1,0,1]
	v_pk_fma_f32 v[52:53], v[92:93], s[6:7], v[52:53] op_sel_hi:[1,0,1]
	s_waitcnt vmcnt(0)
	v_cvt_f32_fp8_e32 v78, v100
	v_cvt_f32_fp8_sdwa v79, v100 src0_sel:BYTE_1
	v_cvt_f32_fp8_sdwa v80, v100 src0_sel:BYTE_2
	v_cvt_f32_fp8_sdwa v81, v100 src0_sel:BYTE_3
	v_cvt_f32_fp8_e32 v82, v101
	v_cvt_f32_fp8_sdwa v83, v101 src0_sel:BYTE_1
	v_cvt_f32_fp8_sdwa v84, v101 src0_sel:BYTE_2
	v_cvt_f32_fp8_sdwa v85, v101 src0_sel:BYTE_3
	v_cvt_f32_fp8_e32 v86, v102
	v_cvt_f32_fp8_sdwa v87, v102 src0_sel:BYTE_1
	v_cvt_f32_fp8_sdwa v88, v102 src0_sel:BYTE_2
	v_cvt_f32_fp8_sdwa v89, v102 src0_sel:BYTE_3
	v_cvt_f32_fp8_e32 v90, v103
	v_cvt_f32_fp8_sdwa v91, v103 src0_sel:BYTE_1
	v_cvt_f32_fp8_sdwa v92, v103 src0_sel:BYTE_2
	v_cvt_f32_fp8_sdwa v93, v103 src0_sel:BYTE_3
	v_pk_fma_f32 v[64:65], v[78:79], s[6:7], v[64:65] op_sel_hi:[1,0,1]
	v_pk_fma_f32 v[62:63], v[80:81], s[6:7], v[62:63] op_sel_hi:[1,0,1]
	v_pk_fma_f32 v[60:61], v[82:83], s[6:7], v[60:61] op_sel_hi:[1,0,1]
	v_pk_fma_f32 v[58:59], v[84:85], s[6:7], v[58:59] op_sel_hi:[1,0,1]
	v_pk_fma_f32 v[56:57], v[86:87], s[6:7], v[56:57] op_sel_hi:[1,0,1]
	v_pk_fma_f32 v[54:55], v[88:89], s[6:7], v[54:55] op_sel_hi:[1,0,1]
	v_pk_fma_f32 v[50:51], v[90:91], s[6:7], v[50:51] op_sel_hi:[1,0,1]
	v_pk_fma_f32 v[52:53], v[92:93], s[6:7], v[52:53] op_sel_hi:[1,0,1]
	s_branch .LBB0_1393
.Lg_cons1:
	s_waitcnt vmcnt(0)
	v_cvt_f32_fp8_e32 v78, v96
	v_cvt_f32_fp8_sdwa v79, v96 src0_sel:BYTE_1
	v_cvt_f32_fp8_sdwa v80, v96 src0_sel:BYTE_2
	v_cvt_f32_fp8_sdwa v81, v96 src0_sel:BYTE_3
	v_cvt_f32_fp8_e32 v82, v97
	v_cvt_f32_fp8_sdwa v83, v97 src0_sel:BYTE_1
	v_cvt_f32_fp8_sdwa v84, v97 src0_sel:BYTE_2
	v_cvt_f32_fp8_sdwa v85, v97 src0_sel:BYTE_3
	v_cvt_f32_fp8_e32 v86, v98
	v_cvt_f32_fp8_sdwa v87, v98 src0_sel:BYTE_1
	v_cvt_f32_fp8_sdwa v88, v98 src0_sel:BYTE_2
	v_cvt_f32_fp8_sdwa v89, v98 src0_sel:BYTE_3
	v_cvt_f32_fp8_e32 v90, v99
	v_cvt_f32_fp8_sdwa v91, v99 src0_sel:BYTE_1
	v_cvt_f32_fp8_sdwa v92, v99 src0_sel:BYTE_2
	v_cvt_f32_fp8_sdwa v93, v99 src0_sel:BYTE_3
	v_pk_fma_f32 v[64:65], v[78:79], s[6:7], v[64:65] op_sel_hi:[1,0,1]
	v_pk_fma_f32 v[62:63], v[80:81], s[6:7], v[62:63] op_sel_hi:[1,0,1]
	v_pk_fma_f32 v[60:61], v[82:83], s[6:7], v[60:61] op_sel_hi:[1,0,1]
	v_pk_fma_f32 v[58:59], v[84:85], s[6:7], v[58:59] op_sel_hi:[1,0,1]
	v_pk_fma_f32 v[56:57], v[86:87], s[6:7], v[56:57] op_sel_hi:[1,0,1]
	v_pk_fma_f32 v[54:55], v[88:89], s[6:7], v[54:55] op_sel_hi:[1,0,1]
	v_pk_fma_f32 v[50:51], v[90:91], s[6:7], v[50:51] op_sel_hi:[1,0,1]
	v_pk_fma_f32 v[52:53], v[92:93], s[6:7], v[52:53] op_sel_hi:[1,0,1]
	s_branch .LBB0_1393
